# ffn2-up conversion beside rwkv_apply handed only to the 192 workgroups that have a single o_gla GEMM tile
# speedup vs baseline: 1.0106x; 1.0007x over previous
.LBB0_990:
	s_and_b64 vcc, exec, s[4:5]
	s_cbranch_vccz .LBB0_1045
	s_mov_b64 s[0:1], -1
	s_and_b64 vcc, exec, s[12:13]
	s_cbranch_vccz .LBB0_1020
	s_sub_i32 s3, s2, 32
	s_lshl_b32 s0, s3, 3
	s_add_i32 s8, s57, s0
	s_waitcnt vmcnt(0)
	v_readlane_b32 s60, v240, 1
	v_readlane_b32 s61, v240, 2
	v_readlane_b32 s62, v240, 3
	v_readlane_b32 s63, v240, 4
	v_readlane_b32 s64, v240, 5
	v_readlane_b32 s65, v240, 6
	v_readlane_b32 s66, v240, 7
	v_readlane_b32 s67, v240, 8
	s_add_i32 s9, s80, 0xffffff00
	s_sub_i32 s8, s8, 0x100
	s_sub_i32 s9, s9, 0x100
	s_mul_i32 s4, s57, 0x2100
	v_lshrrev_b32_e32 v55, 3, v146
	v_and_b32_e32 v56, 7, v146
	v_mul_u32_u24_e32 v44, 0x84, v55
	v_lshl_add_u32 v44, v56, 4, v44
	v_add_u32_e32 v44, s4, v44
	v_add_u32_e32 v45, 0x420, v44
	v_add_u32_e32 v46, 0x840, v44
	v_add_u32_e32 v47, 0xc60, v44
	v_add_u32_e32 v48, 0x1080, v44
	v_add_u32_e32 v49, 0x14a0, v44
	v_add_u32_e32 v50, 0x18c0, v44
	v_add_u32_e32 v51, 0x1ce0, v44
	v_mul_u32_u24_e32 v52, 0x420, v56
	v_lshl_add_u32 v52, v55, 2, v52
	v_add_u32_e32 v52, s4, v52
	v_lshrrev_b32_e32 v55, 3, v146
	v_and_b32_e32 v56, 7, v146
	s_mov_b32 s4, 0x5800
	v_mul_lo_u32 v53, v55, s4
	v_lshl_add_u32 v53, v56, 4, v53
	s_mov_b32 s4, 0x1000
	v_mul_lo_u32 v54, v55, s4
	v_lshl_add_u32 v54, v56, 4, v54
	s_mov_b32 s0, s8
	s_cmp_ge_u32 s0, 0x2c00
	s_cbranch_scc1 .Lcv_done_p7up
	s_lshr_b32 s10, s0, 5
	s_mul_i32 s10, s10, 0x1746
	s_lshr_b32 s10, s10, 16
	s_mul_i32 s11, s10, 352
	s_sub_u32 s11, s0, s11
	s_lshl_b32 s5, s11, 5
	s_lshr_b32 s6, s5, 8
	s_lshl_b32 s6, s6, 7
	s_and_b32 s7, s5, 0x7f
	s_add_u32 s6, s6, s7
	s_bitcmp1_b32 s5, 7
	s_mov_b32 s5, s6
	s_cselect_b32 s12, s64, s62
	s_cselect_b32 s13, s65, s63
	s_mul_i32 s6, s10, 0x160000
	s_lshl_b32 s5, s5, 2
	s_add_u32 s6, s6, s5
	s_add_u32 s12, s12, s6
	s_addc_u32 s13, s13, 0
	global_load_dwordx4 v[64:67], v53, s[12:13] nt
	s_add_u32 s12, s12, 0x2c000
	s_addc_u32 s13, s13, 0
	global_load_dwordx4 v[68:71], v53, s[12:13] nt
	s_add_u32 s12, s12, 0x2c000
	s_addc_u32 s13, s13, 0
	global_load_dwordx4 v[72:75], v53, s[12:13] nt
	s_add_u32 s12, s12, 0x2c000
	s_addc_u32 s13, s13, 0
	global_load_dwordx4 v[76:79], v53, s[12:13] nt
	s_add_u32 s12, s12, 0x2c000
	s_addc_u32 s13, s13, 0
	global_load_dwordx4 v[80:83], v53, s[12:13] nt
	s_add_u32 s12, s12, 0x2c000
	s_addc_u32 s13, s13, 0
	global_load_dwordx4 v[84:87], v53, s[12:13] nt
	s_add_u32 s12, s12, 0x2c000
	s_addc_u32 s13, s13, 0
	global_load_dwordx4 v[88:91], v53, s[12:13] nt
	s_add_u32 s12, s12, 0x2c000
	s_addc_u32 s13, s13, 0
	global_load_dwordx4 v[92:95], v53, s[12:13] nt
	s_add_u32 s1, s0, s9
	s_cmp_ge_u32 s1, 0x2c00
	s_cbranch_scc1 .Lcv_only1_p7up
	s_lshr_b32 s10, s1, 5
	s_mul_i32 s10, s10, 0x1746
	s_lshr_b32 s10, s10, 16
	s_mul_i32 s11, s10, 352
	s_sub_u32 s11, s1, s11
	s_lshl_b32 s5, s11, 5
	s_lshr_b32 s6, s5, 8
	s_lshl_b32 s6, s6, 7
	s_and_b32 s7, s5, 0x7f
	s_add_u32 s6, s6, s7
	s_bitcmp1_b32 s5, 7
	s_mov_b32 s5, s6
	s_cselect_b32 s12, s64, s62
	s_cselect_b32 s13, s65, s63
	s_mul_i32 s6, s10, 0x160000
	s_lshl_b32 s5, s5, 2
	s_add_u32 s6, s6, s5
	s_add_u32 s12, s12, s6
	s_addc_u32 s13, s13, 0
	global_load_dwordx4 v[96:99], v53, s[12:13] nt
	s_add_u32 s12, s12, 0x2c000
	s_addc_u32 s13, s13, 0
	global_load_dwordx4 v[100:103], v53, s[12:13] nt
	s_add_u32 s12, s12, 0x2c000
	s_addc_u32 s13, s13, 0
	global_load_dwordx4 v[104:107], v53, s[12:13] nt
	s_add_u32 s12, s12, 0x2c000
	s_addc_u32 s13, s13, 0
	global_load_dwordx4 v[108:111], v53, s[12:13] nt
	s_add_u32 s12, s12, 0x2c000
	s_addc_u32 s13, s13, 0
	global_load_dwordx4 v[112:115], v53, s[12:13] nt
	s_add_u32 s12, s12, 0x2c000
	s_addc_u32 s13, s13, 0
	global_load_dwordx4 v[116:119], v53, s[12:13] nt
	s_add_u32 s12, s12, 0x2c000
	s_addc_u32 s13, s13, 0
	global_load_dwordx4 v[120:123], v53, s[12:13] nt
	s_add_u32 s12, s12, 0x2c000
	s_addc_u32 s13, s13, 0
	global_load_dwordx4 v[124:127], v53, s[12:13] nt
	s_waitcnt vmcnt(8)
	s_branch .Lcv_procA_p7up
